# conv phase, sample-state halo rows: six f32 loads issued together with counted waits instead of three dependent round trips before the in-phase barrier
# speedup vs baseline: 1.0074x; 1.0074x over previous
; __device__ __forceinline__ const float* pin(int i) { return kargs()->in[i]; }
; __device__ __forceinline__ void phase_conv(const Params& p, int l, const XcdBarrier& xbar) {
;     ...
;     else if (kind == 1) { const float* st = (ssd ? pin(7) : pin(4)) + (size_t)((l * NSB + unit) * 3) * 768 + ch;
; #pragma unroll
;         for (int i = 0; i < 3; ++i) { const f32x4 a = *(const f32x4*)(st + i * 768), b = *(const f32x4*)(st + i * 768 + 4);
;             h[i] = (u32x4){pkh(a[0], a[1]), pkh(a[2], a[3]), pkh(b[0], b[1]), pkh(b[2], b[3])}; } }
.LBB0_460:
	s_or_b64 exec, exec, s[10:11]
	global_load_dwordx2 v[12:13], v[12:13], off
	s_and_b64 s[2:3], s[58:59], exec
	s_cselect_b32 s2, 0x80, 0
	v_add_u32_e32 v14, s2, v78
	s_movk_i32 s2, 0x2400
	v_mul_lo_u32 v16, v14, s2
	s_mov_b64 s[2:3], 0x1800
	s_waitcnt vmcnt(0)
	v_lshl_add_u64 v[12:13], v[12:13], 0, v[16:17]
	v_lshl_add_u64 v[44:45], v[148:149], 2, v[12:13]
	v_lshl_add_u64 v[48:49], v[44:45], 0, s[2:3]
	global_load_dwordx4 v[12:15], v[44:45], off
	global_load_dwordx4 v[38:41], v[44:45], off offset:16
	global_load_dwordx4 v[54:57], v[44:45], off offset:3072
	global_load_dwordx4 v[58:61], v[44:45], off offset:3088
	global_load_dwordx4 v[62:65], v[48:49], off offset:16
	global_load_dwordx4 v[42:45], v[48:49], off
	s_movk_i32 s2, 0x1000
	s_waitcnt vmcnt(4)
	v_cvt_pk_f16_f32 v12, v12, v13
	v_cvt_pk_f16_f32 v13, v14, v15
	v_cvt_pk_f16_f32 v14, v38, v39
	v_cvt_pk_f16_f32 v15, v40, v41
	s_waitcnt vmcnt(2)
	v_cvt_pk_f16_f32 v38, v54, v55
	v_cvt_pk_f16_f32 v39, v56, v57
	v_cvt_pk_f16_f32 v40, v58, v59
	v_cvt_pk_f16_f32 v41, v60, v61
	s_waitcnt vmcnt(0)
	v_cvt_pk_f16_f32 v42, v42, v43
	v_cvt_pk_f16_f32 v43, v44, v45
	v_cvt_pk_f16_f32 v44, v62, v63
	v_cvt_pk_f16_f32 v45, v64, v65
